# FFN1 epilogue: rows regrouped across lanes with ds_bpermute so each lane stores 16 contiguous bytes (8 dwordx4 stores per wave instead of 16 dwordx2), SGPR-base store addressing
# baseline (speedup 1.0000x reference)
.LBB0_97:
	s_or_b64 exec, exec, s[22:23]
	s_cmp_gt_i32 s30, 0
	s_waitcnt lgkmcnt(0)
	s_barrier
	v_cmp_eq_u32_e64 s[42:43], 0, v132
	v_cmp_eq_u32_e64 s[40:41], 15, v132
	v_lshlrev_b32_e32 v230, 2, v172
	v_add_u32_e32 v230, 0x22400, v230
	s_lshl_b32 s100, s29, 8
	s_lshl_b32 s101, s30, 6
	s_add_i32 s100, s100, s101
	v_lshl_add_u32 v231, v133, 4, v132
	v_lshrrev_b32_e32 v232, 2, v231
	v_and_b32_e32 v233, 3, v231
	v_lshlrev_b32_e32 v235, 2, v232
	v_lshl_add_u32 v235, v233, 6, v235
	v_add_u32_e32 v232, s100, v232
	v_mul_lo_u32 v234, v232, s15
	v_lshlrev_b32_e32 v232, 3, v133
	v_sub_u32_e32 v232, v172, v232
	v_lshl_add_u32 v232, v233, 3, v232
	v_lshl_add_u32 v234, v232, 1, v234
	v_mov_b32_e32 v232, 1.0
	s_lshl_b64 s[100:101], s[0:1], 1
	s_add_u32 s22, s16, s100
	s_addc_u32 s23, s17, s101
	ds_read_b128 v[190:193], v230 offset:0
	ds_read_b128 v[194:197], v230 offset:512
	ds_read_b128 v[198:201], v230 offset:1024
	ds_read_b128 v[208:211], v230 offset:1536
	ds_read_b128 v[212:215], v230 offset:2048
	ds_read_b128 v[216:219], v230 offset:2560
	ds_read_b128 v[220:223], v230 offset:3072
	ds_read_b128 v[224:227], v230 offset:3584
	s_cmp_eq_u32 s30, 0
	s_cbranch_scc1 .Lffn1c_1
	s_lshl_b32 s100, s30, 11
	s_sub_i32 s100, s100, 0x400
	v_add_u32_e32 v231, s100, v189
	ds_read_b128 v[130:133], v231 offset:0
	ds_read_b128 v[134:137], v231 offset:512
	s_branch .Lffn1c_2

.Lffn1c_2:
	s_lshl_b32 s100, s30, 11
	s_add_i32 s100, s100, 0x800
	v_add_u32_e32 v231, s100, v189
	ds_read_b128 v[138:141], v231 offset:0
	ds_read_b128 v[142:145], v231 offset:512
	s_waitcnt lgkmcnt(0)
	v_cndmask_b32_e64 v150, v126, v130, s[40:41]
	v_cndmask_b32_e64 v151, v127, v131, s[40:41]
	v_cndmask_b32_e64 v152, v128, v132, s[40:41]
	v_cndmask_b32_e64 v153, v129, v133, s[40:41]
	v_cndmask_b32_e64 v154, v126, v118, s[42:43]
	v_cndmask_b32_e64 v155, v127, v119, s[42:43]
	v_cndmask_b32_e64 v156, v128, v120, s[42:43]
	v_cndmask_b32_e64 v157, v129, v121, s[42:43]
	v_pk_fma_f32 v[122:123], v[126:127], v[198:199], v[220:221]
	v_pk_fma_f32 v[124:125], v[128:129], v[200:201], v[222:223]
	v_fmac_f32_dpp v122, v150, v190 row_ror:1 row_mask:0xf bank_mask:0xf
	v_fmac_f32_dpp v123, v151, v191 row_ror:1 row_mask:0xf bank_mask:0xf
	v_fmac_f32_dpp v124, v152, v192 row_ror:1 row_mask:0xf bank_mask:0xf
	v_fmac_f32_dpp v125, v153, v193 row_ror:1 row_mask:0xf bank_mask:0xf
	v_fmac_f32_dpp v122, v154, v212 row_ror:15 row_mask:0xf bank_mask:0xf
	v_fmac_f32_dpp v123, v155, v213 row_ror:15 row_mask:0xf bank_mask:0xf
	v_fmac_f32_dpp v124, v156, v214 row_ror:15 row_mask:0xf bank_mask:0xf
	v_fmac_f32_dpp v125, v157, v215 row_ror:15 row_mask:0xf bank_mask:0xf
	v_cndmask_b32_e64 v150, v146, v134, s[40:41]
	v_cndmask_b32_e64 v151, v147, v135, s[40:41]
	v_cndmask_b32_e64 v152, v148, v136, s[40:41]
	v_cndmask_b32_e64 v153, v149, v137, s[40:41]
	v_cndmask_b32_e64 v154, v146, v114, s[42:43]
	v_cndmask_b32_e64 v155, v147, v115, s[42:43]
	v_cndmask_b32_e64 v156, v148, v116, s[42:43]
	v_cndmask_b32_e64 v157, v149, v117, s[42:43]
	v_pk_fma_f32 v[158:159], v[146:147], v[208:209], v[224:225]
	v_pk_fma_f32 v[160:161], v[148:149], v[210:211], v[226:227]
	v_fmac_f32_dpp v158, v150, v194 row_ror:1 row_mask:0xf bank_mask:0xf
	v_fmac_f32_dpp v159, v151, v195 row_ror:1 row_mask:0xf bank_mask:0xf
	v_fmac_f32_dpp v160, v152, v196 row_ror:1 row_mask:0xf bank_mask:0xf
	v_fmac_f32_dpp v161, v153, v197 row_ror:1 row_mask:0xf bank_mask:0xf
	v_fmac_f32_dpp v158, v154, v216 row_ror:15 row_mask:0xf bank_mask:0xf
	v_fmac_f32_dpp v159, v155, v217 row_ror:15 row_mask:0xf bank_mask:0xf
	v_fmac_f32_dpp v160, v156, v218 row_ror:15 row_mask:0xf bank_mask:0xf
	v_fmac_f32_dpp v161, v157, v219 row_ror:15 row_mask:0xf bank_mask:0xf
	s_cmp_eq_u32 s30, 0
	s_cbranch_scc1 .Lffn1c_3
	s_lshl_b32 s100, s30, 11
	s_sub_i32 s100, s100, 0x400
	v_add_u32_e32 v231, s100, v189
	ds_read_b128 v[130:133], v231 offset:16
	ds_read_b128 v[134:137], v231 offset:528
	s_branch .Lffn1c_4

.Lffn1c_4:
	v_exp_f32_e32 v172, v122
	v_exp_f32_e32 v173, v123
	v_exp_f32_e32 v174, v124
	v_exp_f32_e32 v175, v125
	v_pk_add_f32 v[172:173], v[172:173], v[232:233] op_sel_hi:[1,0]
	v_pk_add_f32 v[174:175], v[174:175], v[232:233] op_sel_hi:[1,0]
	v_rcp_f32_e32 v172, v172
	v_rcp_f32_e32 v173, v173
	v_rcp_f32_e32 v174, v174
	v_rcp_f32_e32 v175, v175
	v_pk_mul_f32 v[122:123], v[122:123], v[158:159]
	v_pk_mul_f32 v[124:125], v[124:125], v[160:161]
	v_pk_mul_f32 v[172:173], v[172:173], v[122:123]
	v_pk_mul_f32 v[174:175], v[174:175], v[124:125]
	v_cvt_pk_bf16_f32 v240, v172, v173
	v_cvt_pk_bf16_f32 v241, v174, v175
	v_cndmask_b32_e64 v150, v118, v126, s[40:41]
	v_cndmask_b32_e64 v151, v119, v127, s[40:41]
	v_cndmask_b32_e64 v152, v120, v128, s[40:41]
	v_cndmask_b32_e64 v153, v121, v129, s[40:41]
	v_cndmask_b32_e64 v154, v118, v110, s[42:43]
	v_cndmask_b32_e64 v155, v119, v111, s[42:43]
	v_cndmask_b32_e64 v156, v120, v112, s[42:43]
	v_cndmask_b32_e64 v157, v121, v113, s[42:43]
	v_pk_fma_f32 v[122:123], v[118:119], v[198:199], v[220:221]
	v_pk_fma_f32 v[124:125], v[120:121], v[200:201], v[222:223]
	v_fmac_f32_dpp v122, v150, v190 row_ror:1 row_mask:0xf bank_mask:0xf
	v_fmac_f32_dpp v123, v151, v191 row_ror:1 row_mask:0xf bank_mask:0xf
	v_fmac_f32_dpp v124, v152, v192 row_ror:1 row_mask:0xf bank_mask:0xf
	v_fmac_f32_dpp v125, v153, v193 row_ror:1 row_mask:0xf bank_mask:0xf
	v_fmac_f32_dpp v122, v154, v212 row_ror:15 row_mask:0xf bank_mask:0xf
	v_fmac_f32_dpp v123, v155, v213 row_ror:15 row_mask:0xf bank_mask:0xf
	v_fmac_f32_dpp v124, v156, v214 row_ror:15 row_mask:0xf bank_mask:0xf
	v_fmac_f32_dpp v125, v157, v215 row_ror:15 row_mask:0xf bank_mask:0xf
	v_cndmask_b32_e64 v150, v114, v146, s[40:41]
	v_cndmask_b32_e64 v151, v115, v147, s[40:41]
	v_cndmask_b32_e64 v152, v116, v148, s[40:41]
	v_cndmask_b32_e64 v153, v117, v149, s[40:41]
	v_cndmask_b32_e64 v154, v114, v106, s[42:43]
	v_cndmask_b32_e64 v155, v115, v107, s[42:43]
	v_cndmask_b32_e64 v156, v116, v108, s[42:43]
	v_cndmask_b32_e64 v157, v117, v109, s[42:43]
	v_pk_fma_f32 v[158:159], v[114:115], v[208:209], v[224:225]
	v_pk_fma_f32 v[160:161], v[116:117], v[210:211], v[226:227]
	v_fmac_f32_dpp v158, v150, v194 row_ror:1 row_mask:0xf bank_mask:0xf
	v_fmac_f32_dpp v159, v151, v195 row_ror:1 row_mask:0xf bank_mask:0xf
	v_fmac_f32_dpp v160, v152, v196 row_ror:1 row_mask:0xf bank_mask:0xf
	v_fmac_f32_dpp v161, v153, v197 row_ror:1 row_mask:0xf bank_mask:0xf
	v_fmac_f32_dpp v158, v154, v216 row_ror:15 row_mask:0xf bank_mask:0xf
	v_fmac_f32_dpp v159, v155, v217 row_ror:15 row_mask:0xf bank_mask:0xf
	v_fmac_f32_dpp v160, v156, v218 row_ror:15 row_mask:0xf bank_mask:0xf
	v_fmac_f32_dpp v161, v157, v219 row_ror:15 row_mask:0xf bank_mask:0xf
	v_exp_f32_e32 v172, v122
	v_exp_f32_e32 v173, v123
	v_exp_f32_e32 v174, v124
	v_exp_f32_e32 v175, v125
	v_pk_add_f32 v[172:173], v[172:173], v[232:233] op_sel_hi:[1,0]
	v_pk_add_f32 v[174:175], v[174:175], v[232:233] op_sel_hi:[1,0]
	v_rcp_f32_e32 v172, v172
	v_rcp_f32_e32 v173, v173
	v_rcp_f32_e32 v174, v174
	v_rcp_f32_e32 v175, v175
	v_pk_mul_f32 v[122:123], v[122:123], v[158:159]
	v_pk_mul_f32 v[124:125], v[124:125], v[160:161]
	v_pk_mul_f32 v[172:173], v[172:173], v[122:123]
	v_pk_mul_f32 v[174:175], v[174:175], v[124:125]
	v_cvt_pk_bf16_f32 v242, v172, v173
	v_cvt_pk_bf16_f32 v243, v174, v175
	v_cndmask_b32_e64 v150, v110, v118, s[40:41]
	v_cndmask_b32_e64 v151, v111, v119, s[40:41]
	v_cndmask_b32_e64 v152, v112, v120, s[40:41]
	v_cndmask_b32_e64 v153, v113, v121, s[40:41]
	v_cndmask_b32_e64 v154, v110, v102, s[42:43]
	v_cndmask_b32_e64 v155, v111, v103, s[42:43]
	v_cndmask_b32_e64 v156, v112, v104, s[42:43]
	v_cndmask_b32_e64 v157, v113, v105, s[42:43]
	v_pk_fma_f32 v[122:123], v[110:111], v[198:199], v[220:221]
	v_pk_fma_f32 v[124:125], v[112:113], v[200:201], v[222:223]
	v_fmac_f32_dpp v122, v150, v190 row_ror:1 row_mask:0xf bank_mask:0xf
	v_fmac_f32_dpp v123, v151, v191 row_ror:1 row_mask:0xf bank_mask:0xf
	v_fmac_f32_dpp v124, v152, v192 row_ror:1 row_mask:0xf bank_mask:0xf
	v_fmac_f32_dpp v125, v153, v193 row_ror:1 row_mask:0xf bank_mask:0xf
	v_fmac_f32_dpp v122, v154, v212 row_ror:15 row_mask:0xf bank_mask:0xf
	v_fmac_f32_dpp v123, v155, v213 row_ror:15 row_mask:0xf bank_mask:0xf
	v_fmac_f32_dpp v124, v156, v214 row_ror:15 row_mask:0xf bank_mask:0xf
	v_fmac_f32_dpp v125, v157, v215 row_ror:15 row_mask:0xf bank_mask:0xf
	v_cndmask_b32_e64 v150, v106, v114, s[40:41]
	v_cndmask_b32_e64 v151, v107, v115, s[40:41]
	v_cndmask_b32_e64 v152, v108, v116, s[40:41]
	v_cndmask_b32_e64 v153, v109, v117, s[40:41]
	v_cndmask_b32_e64 v154, v106, v98, s[42:43]
	v_cndmask_b32_e64 v155, v107, v99, s[42:43]
	v_cndmask_b32_e64 v156, v108, v100, s[42:43]
	v_cndmask_b32_e64 v157, v109, v101, s[42:43]
	v_pk_fma_f32 v[158:159], v[106:107], v[208:209], v[224:225]
	v_pk_fma_f32 v[160:161], v[108:109], v[210:211], v[226:227]
	v_fmac_f32_dpp v158, v150, v194 row_ror:1 row_mask:0xf bank_mask:0xf
	v_fmac_f32_dpp v159, v151, v195 row_ror:1 row_mask:0xf bank_mask:0xf
	v_fmac_f32_dpp v160, v152, v196 row_ror:1 row_mask:0xf bank_mask:0xf
	v_fmac_f32_dpp v161, v153, v197 row_ror:1 row_mask:0xf bank_mask:0xf
	v_fmac_f32_dpp v158, v154, v216 row_ror:15 row_mask:0xf bank_mask:0xf
	v_fmac_f32_dpp v159, v155, v217 row_ror:15 row_mask:0xf bank_mask:0xf
	v_fmac_f32_dpp v160, v156, v218 row_ror:15 row_mask:0xf bank_mask:0xf
	v_fmac_f32_dpp v161, v157, v219 row_ror:15 row_mask:0xf bank_mask:0xf
	v_exp_f32_e32 v172, v122
	v_exp_f32_e32 v173, v123
	v_exp_f32_e32 v174, v124
	v_exp_f32_e32 v175, v125
	v_pk_add_f32 v[172:173], v[172:173], v[232:233] op_sel_hi:[1,0]
	v_pk_add_f32 v[174:175], v[174:175], v[232:233] op_sel_hi:[1,0]
	v_rcp_f32_e32 v172, v172
	v_rcp_f32_e32 v173, v173
	v_rcp_f32_e32 v174, v174
	v_rcp_f32_e32 v175, v175
	v_pk_mul_f32 v[122:123], v[122:123], v[158:159]
	v_pk_mul_f32 v[124:125], v[124:125], v[160:161]
	v_pk_mul_f32 v[172:173], v[172:173], v[122:123]
	v_pk_mul_f32 v[174:175], v[174:175], v[124:125]
	v_cvt_pk_bf16_f32 v244, v172, v173
	v_cvt_pk_bf16_f32 v245, v174, v175
	s_waitcnt lgkmcnt(0)
	v_cndmask_b32_e64 v150, v102, v110, s[40:41]
	v_cndmask_b32_e64 v151, v103, v111, s[40:41]
	v_cndmask_b32_e64 v152, v104, v112, s[40:41]
	v_cndmask_b32_e64 v153, v105, v113, s[40:41]
	v_cndmask_b32_e64 v154, v102, v138, s[42:43]
	v_cndmask_b32_e64 v155, v103, v139, s[42:43]
	v_cndmask_b32_e64 v156, v104, v140, s[42:43]
	v_cndmask_b32_e64 v157, v105, v141, s[42:43]
	v_pk_fma_f32 v[122:123], v[102:103], v[198:199], v[220:221]
	v_pk_fma_f32 v[124:125], v[104:105], v[200:201], v[222:223]
	v_fmac_f32_dpp v122, v150, v190 row_ror:1 row_mask:0xf bank_mask:0xf
	v_fmac_f32_dpp v123, v151, v191 row_ror:1 row_mask:0xf bank_mask:0xf
	v_fmac_f32_dpp v124, v152, v192 row_ror:1 row_mask:0xf bank_mask:0xf
	v_fmac_f32_dpp v125, v153, v193 row_ror:1 row_mask:0xf bank_mask:0xf
	v_fmac_f32_dpp v122, v154, v212 row_ror:15 row_mask:0xf bank_mask:0xf
	v_fmac_f32_dpp v123, v155, v213 row_ror:15 row_mask:0xf bank_mask:0xf
	v_fmac_f32_dpp v124, v156, v214 row_ror:15 row_mask:0xf bank_mask:0xf
	v_fmac_f32_dpp v125, v157, v215 row_ror:15 row_mask:0xf bank_mask:0xf
	v_cndmask_b32_e64 v150, v98, v106, s[40:41]
	v_cndmask_b32_e64 v151, v99, v107, s[40:41]
	v_cndmask_b32_e64 v152, v100, v108, s[40:41]
	v_cndmask_b32_e64 v153, v101, v109, s[40:41]
	v_cndmask_b32_e64 v154, v98, v142, s[42:43]
	v_cndmask_b32_e64 v155, v99, v143, s[42:43]
	v_cndmask_b32_e64 v156, v100, v144, s[42:43]
	v_cndmask_b32_e64 v157, v101, v145, s[42:43]
	v_pk_fma_f32 v[158:159], v[98:99], v[208:209], v[224:225]
	v_pk_fma_f32 v[160:161], v[100:101], v[210:211], v[226:227]
	v_fmac_f32_dpp v158, v150, v194 row_ror:1 row_mask:0xf bank_mask:0xf
	v_fmac_f32_dpp v159, v151, v195 row_ror:1 row_mask:0xf bank_mask:0xf
	v_fmac_f32_dpp v160, v152, v196 row_ror:1 row_mask:0xf bank_mask:0xf
	v_fmac_f32_dpp v161, v153, v197 row_ror:1 row_mask:0xf bank_mask:0xf
	v_fmac_f32_dpp v158, v154, v216 row_ror:15 row_mask:0xf bank_mask:0xf
	v_fmac_f32_dpp v159, v155, v217 row_ror:15 row_mask:0xf bank_mask:0xf
	v_fmac_f32_dpp v160, v156, v218 row_ror:15 row_mask:0xf bank_mask:0xf
	v_fmac_f32_dpp v161, v157, v219 row_ror:15 row_mask:0xf bank_mask:0xf
	s_lshl_b32 s100, s30, 11
	s_add_i32 s100, s100, 0x800
	v_add_u32_e32 v231, s100, v189
	ds_read_b128 v[138:141], v231 offset:16
	ds_read_b128 v[142:145], v231 offset:528
	ds_read_b128 v[126:129], v230 offset:16
	ds_read_b128 v[146:149], v230 offset:528
	ds_read_b128 v[118:121], v230 offset:1040
	ds_read_b128 v[114:117], v230 offset:1552
	ds_read_b128 v[110:113], v230 offset:2064
	ds_read_b128 v[106:109], v230 offset:2576
	ds_read_b128 v[102:105], v230 offset:3088
	ds_read_b128 v[98:101], v230 offset:3600
	v_exp_f32_e32 v172, v122
	v_exp_f32_e32 v173, v123
	v_exp_f32_e32 v174, v124
	v_exp_f32_e32 v175, v125
	v_pk_add_f32 v[172:173], v[172:173], v[232:233] op_sel_hi:[1,0]
	v_pk_add_f32 v[174:175], v[174:175], v[232:233] op_sel_hi:[1,0]
	v_rcp_f32_e32 v172, v172
	v_rcp_f32_e32 v173, v173
	v_rcp_f32_e32 v174, v174
	v_rcp_f32_e32 v175, v175
	v_pk_mul_f32 v[122:123], v[122:123], v[158:159]
	v_pk_mul_f32 v[124:125], v[124:125], v[160:161]
	v_pk_mul_f32 v[172:173], v[172:173], v[122:123]
	v_pk_mul_f32 v[174:175], v[174:175], v[124:125]
	v_cvt_pk_bf16_f32 v246, v172, v173
	v_cvt_pk_bf16_f32 v247, v174, v175
	s_waitcnt lgkmcnt(0)
	v_cndmask_b32_e64 v150, v62, v130, s[40:41]
	v_cndmask_b32_e64 v151, v63, v131, s[40:41]
	v_cndmask_b32_e64 v152, v64, v132, s[40:41]
	v_cndmask_b32_e64 v153, v65, v133, s[40:41]
	v_cndmask_b32_e64 v154, v62, v54, s[42:43]
	v_cndmask_b32_e64 v155, v63, v55, s[42:43]
	v_cndmask_b32_e64 v156, v64, v56, s[42:43]
	v_cndmask_b32_e64 v157, v65, v57, s[42:43]
	v_pk_fma_f32 v[122:123], v[62:63], v[118:119], v[102:103]
	v_pk_fma_f32 v[124:125], v[64:65], v[120:121], v[104:105]
	v_fmac_f32_dpp v122, v150, v126 row_ror:1 row_mask:0xf bank_mask:0xf
	v_fmac_f32_dpp v123, v151, v127 row_ror:1 row_mask:0xf bank_mask:0xf
	v_fmac_f32_dpp v124, v152, v128 row_ror:1 row_mask:0xf bank_mask:0xf
	v_fmac_f32_dpp v125, v153, v129 row_ror:1 row_mask:0xf bank_mask:0xf
	v_fmac_f32_dpp v122, v154, v110 row_ror:15 row_mask:0xf bank_mask:0xf
	v_fmac_f32_dpp v123, v155, v111 row_ror:15 row_mask:0xf bank_mask:0xf
	v_fmac_f32_dpp v124, v156, v112 row_ror:15 row_mask:0xf bank_mask:0xf
	v_fmac_f32_dpp v125, v157, v113 row_ror:15 row_mask:0xf bank_mask:0xf
	v_cndmask_b32_e64 v150, v58, v134, s[40:41]
	v_cndmask_b32_e64 v151, v59, v135, s[40:41]
	v_cndmask_b32_e64 v152, v60, v136, s[40:41]
	v_cndmask_b32_e64 v153, v61, v137, s[40:41]
	v_cndmask_b32_e64 v154, v58, v50, s[42:43]
	v_cndmask_b32_e64 v155, v59, v51, s[42:43]
	v_cndmask_b32_e64 v156, v60, v52, s[42:43]
	v_cndmask_b32_e64 v157, v61, v53, s[42:43]
	v_pk_fma_f32 v[158:159], v[58:59], v[114:115], v[98:99]
	v_pk_fma_f32 v[160:161], v[60:61], v[116:117], v[100:101]
	v_fmac_f32_dpp v158, v150, v146 row_ror:1 row_mask:0xf bank_mask:0xf
	v_fmac_f32_dpp v159, v151, v147 row_ror:1 row_mask:0xf bank_mask:0xf
	v_fmac_f32_dpp v160, v152, v148 row_ror:1 row_mask:0xf bank_mask:0xf
	v_fmac_f32_dpp v161, v153, v149 row_ror:1 row_mask:0xf bank_mask:0xf
	v_fmac_f32_dpp v158, v154, v106 row_ror:15 row_mask:0xf bank_mask:0xf
	v_fmac_f32_dpp v159, v155, v107 row_ror:15 row_mask:0xf bank_mask:0xf
	v_fmac_f32_dpp v160, v156, v108 row_ror:15 row_mask:0xf bank_mask:0xf
	v_fmac_f32_dpp v161, v157, v109 row_ror:15 row_mask:0xf bank_mask:0xf
	s_lshl_b32 s100, s30, 11
	s_add_i32 s100, s100, 0xc00
	v_add_u32_e32 v231, s100, v189
	ds_read_b128 v[130:133], v231 offset:0
	ds_read_b128 v[134:137], v231 offset:512
	v_exp_f32_e32 v172, v122
	v_exp_f32_e32 v173, v123
	v_exp_f32_e32 v174, v124
	v_exp_f32_e32 v175, v125
	v_pk_add_f32 v[172:173], v[172:173], v[232:233] op_sel_hi:[1,0]
	v_pk_add_f32 v[174:175], v[174:175], v[232:233] op_sel_hi:[1,0]
	v_rcp_f32_e32 v172, v172
	v_rcp_f32_e32 v173, v173
	v_rcp_f32_e32 v174, v174
	v_rcp_f32_e32 v175, v175
	v_pk_mul_f32 v[122:123], v[122:123], v[158:159]
	v_pk_mul_f32 v[124:125], v[124:125], v[160:161]
	v_pk_mul_f32 v[172:173], v[172:173], v[122:123]
	v_pk_mul_f32 v[174:175], v[174:175], v[124:125]
	v_cvt_pk_bf16_f32 v228, v172, v173
	v_cvt_pk_bf16_f32 v229, v174, v175
	ds_bpermute_b32 v236, v235, v240
	ds_bpermute_b32 v237, v235, v241
	ds_bpermute_b32 v238, v235, v228
	ds_bpermute_b32 v239, v235, v229
	v_cndmask_b32_e64 v150, v54, v62, s[40:41]
	v_cndmask_b32_e64 v151, v55, v63, s[40:41]
	v_cndmask_b32_e64 v152, v56, v64, s[40:41]
	v_cndmask_b32_e64 v153, v57, v65, s[40:41]
	v_cndmask_b32_e64 v154, v54, v46, s[42:43]
	v_cndmask_b32_e64 v155, v55, v47, s[42:43]
	v_cndmask_b32_e64 v156, v56, v48, s[42:43]
	v_cndmask_b32_e64 v157, v57, v49, s[42:43]
	v_pk_fma_f32 v[122:123], v[54:55], v[118:119], v[102:103]
	v_pk_fma_f32 v[124:125], v[56:57], v[120:121], v[104:105]
	v_fmac_f32_dpp v122, v150, v126 row_ror:1 row_mask:0xf bank_mask:0xf
	v_fmac_f32_dpp v123, v151, v127 row_ror:1 row_mask:0xf bank_mask:0xf
	v_fmac_f32_dpp v124, v152, v128 row_ror:1 row_mask:0xf bank_mask:0xf
	v_fmac_f32_dpp v125, v153, v129 row_ror:1 row_mask:0xf bank_mask:0xf
	v_fmac_f32_dpp v122, v154, v110 row_ror:15 row_mask:0xf bank_mask:0xf
	v_fmac_f32_dpp v123, v155, v111 row_ror:15 row_mask:0xf bank_mask:0xf
	v_fmac_f32_dpp v124, v156, v112 row_ror:15 row_mask:0xf bank_mask:0xf
	v_fmac_f32_dpp v125, v157, v113 row_ror:15 row_mask:0xf bank_mask:0xf
	v_cndmask_b32_e64 v150, v50, v58, s[40:41]
	v_cndmask_b32_e64 v151, v51, v59, s[40:41]
	v_cndmask_b32_e64 v152, v52, v60, s[40:41]
	v_cndmask_b32_e64 v153, v53, v61, s[40:41]
	v_cndmask_b32_e64 v154, v50, v42, s[42:43]
	v_cndmask_b32_e64 v155, v51, v43, s[42:43]
	v_cndmask_b32_e64 v156, v52, v44, s[42:43]
	v_cndmask_b32_e64 v157, v53, v45, s[42:43]
	v_pk_fma_f32 v[158:159], v[50:51], v[114:115], v[98:99]
	v_pk_fma_f32 v[160:161], v[52:53], v[116:117], v[100:101]
	v_fmac_f32_dpp v158, v150, v146 row_ror:1 row_mask:0xf bank_mask:0xf
	v_fmac_f32_dpp v159, v151, v147 row_ror:1 row_mask:0xf bank_mask:0xf
	v_fmac_f32_dpp v160, v152, v148 row_ror:1 row_mask:0xf bank_mask:0xf
	v_fmac_f32_dpp v161, v153, v149 row_ror:1 row_mask:0xf bank_mask:0xf
	v_fmac_f32_dpp v158, v154, v106 row_ror:15 row_mask:0xf bank_mask:0xf
	v_fmac_f32_dpp v159, v155, v107 row_ror:15 row_mask:0xf bank_mask:0xf
	v_fmac_f32_dpp v160, v156, v108 row_ror:15 row_mask:0xf bank_mask:0xf
	v_fmac_f32_dpp v161, v157, v109 row_ror:15 row_mask:0xf bank_mask:0xf
	s_add_u32 s26, s22, 0x0
	s_addc_u32 s27, s23, 0
	s_waitcnt lgkmcnt(0)
	global_store_dwordx4 v234, v[236:239], s[26:27]
	v_exp_f32_e32 v172, v122
	v_exp_f32_e32 v173, v123
	v_exp_f32_e32 v174, v124
	v_exp_f32_e32 v175, v125
	v_pk_add_f32 v[172:173], v[172:173], v[232:233] op_sel_hi:[1,0]
	v_pk_add_f32 v[174:175], v[174:175], v[232:233] op_sel_hi:[1,0]
	v_rcp_f32_e32 v172, v172
	v_rcp_f32_e32 v173, v173
	v_rcp_f32_e32 v174, v174
	v_rcp_f32_e32 v175, v175
	v_pk_mul_f32 v[122:123], v[122:123], v[158:159]
	v_pk_mul_f32 v[124:125], v[124:125], v[160:161]
	v_pk_mul_f32 v[172:173], v[172:173], v[122:123]
	v_pk_mul_f32 v[174:175], v[174:175], v[124:125]
	v_cvt_pk_bf16_f32 v228, v172, v173
	v_cvt_pk_bf16_f32 v229, v174, v175
	ds_bpermute_b32 v236, v235, v242
	ds_bpermute_b32 v237, v235, v243
	ds_bpermute_b32 v238, v235, v228
	ds_bpermute_b32 v239, v235, v229
	v_cndmask_b32_e64 v150, v46, v54, s[40:41]
	v_cndmask_b32_e64 v151, v47, v55, s[40:41]
	v_cndmask_b32_e64 v152, v48, v56, s[40:41]
	v_cndmask_b32_e64 v153, v49, v57, s[40:41]
	v_cndmask_b32_e64 v154, v46, v38, s[42:43]
	v_cndmask_b32_e64 v155, v47, v39, s[42:43]
	v_cndmask_b32_e64 v156, v48, v40, s[42:43]
	v_cndmask_b32_e64 v157, v49, v41, s[42:43]
	v_pk_fma_f32 v[122:123], v[46:47], v[118:119], v[102:103]
	v_pk_fma_f32 v[124:125], v[48:49], v[120:121], v[104:105]
	v_fmac_f32_dpp v122, v150, v126 row_ror:1 row_mask:0xf bank_mask:0xf
	v_fmac_f32_dpp v123, v151, v127 row_ror:1 row_mask:0xf bank_mask:0xf
	v_fmac_f32_dpp v124, v152, v128 row_ror:1 row_mask:0xf bank_mask:0xf
	v_fmac_f32_dpp v125, v153, v129 row_ror:1 row_mask:0xf bank_mask:0xf
	v_fmac_f32_dpp v122, v154, v110 row_ror:15 row_mask:0xf bank_mask:0xf
	v_fmac_f32_dpp v123, v155, v111 row_ror:15 row_mask:0xf bank_mask:0xf
	v_fmac_f32_dpp v124, v156, v112 row_ror:15 row_mask:0xf bank_mask:0xf
	v_fmac_f32_dpp v125, v157, v113 row_ror:15 row_mask:0xf bank_mask:0xf
	v_cndmask_b32_e64 v150, v42, v50, s[40:41]
	v_cndmask_b32_e64 v151, v43, v51, s[40:41]
	v_cndmask_b32_e64 v152, v44, v52, s[40:41]
	v_cndmask_b32_e64 v153, v45, v53, s[40:41]
	v_cndmask_b32_e64 v154, v42, v34, s[42:43]
	v_cndmask_b32_e64 v155, v43, v35, s[42:43]
	v_cndmask_b32_e64 v156, v44, v36, s[42:43]
	v_cndmask_b32_e64 v157, v45, v37, s[42:43]
	v_pk_fma_f32 v[158:159], v[42:43], v[114:115], v[98:99]
	v_pk_fma_f32 v[160:161], v[44:45], v[116:117], v[100:101]
	v_fmac_f32_dpp v158, v150, v146 row_ror:1 row_mask:0xf bank_mask:0xf
	v_fmac_f32_dpp v159, v151, v147 row_ror:1 row_mask:0xf bank_mask:0xf
	v_fmac_f32_dpp v160, v152, v148 row_ror:1 row_mask:0xf bank_mask:0xf
	v_fmac_f32_dpp v161, v153, v149 row_ror:1 row_mask:0xf bank_mask:0xf
	v_fmac_f32_dpp v158, v154, v106 row_ror:15 row_mask:0xf bank_mask:0xf
	v_fmac_f32_dpp v159, v155, v107 row_ror:15 row_mask:0xf bank_mask:0xf
	v_fmac_f32_dpp v160, v156, v108 row_ror:15 row_mask:0xf bank_mask:0xf
	v_fmac_f32_dpp v161, v157, v109 row_ror:15 row_mask:0xf bank_mask:0xf
	s_add_u32 s26, s22, 0x16000
	s_addc_u32 s27, s23, 0
	s_waitcnt lgkmcnt(0)
	global_store_dwordx4 v234, v[236:239], s[26:27]
	v_exp_f32_e32 v172, v122
	v_exp_f32_e32 v173, v123
	v_exp_f32_e32 v174, v124
	v_exp_f32_e32 v175, v125
	v_pk_add_f32 v[172:173], v[172:173], v[232:233] op_sel_hi:[1,0]
	v_pk_add_f32 v[174:175], v[174:175], v[232:233] op_sel_hi:[1,0]
	v_rcp_f32_e32 v172, v172
	v_rcp_f32_e32 v173, v173
	v_rcp_f32_e32 v174, v174
	v_rcp_f32_e32 v175, v175
	v_pk_mul_f32 v[122:123], v[122:123], v[158:159]
	v_pk_mul_f32 v[124:125], v[124:125], v[160:161]
	v_pk_mul_f32 v[172:173], v[172:173], v[122:123]
	v_pk_mul_f32 v[174:175], v[174:175], v[124:125]
	v_cvt_pk_bf16_f32 v228, v172, v173
	v_cvt_pk_bf16_f32 v229, v174, v175
	ds_bpermute_b32 v236, v235, v244
	ds_bpermute_b32 v237, v235, v245
	ds_bpermute_b32 v238, v235, v228
	ds_bpermute_b32 v239, v235, v229
	s_waitcnt lgkmcnt(0)
	v_cndmask_b32_e64 v150, v38, v46, s[40:41]
	v_cndmask_b32_e64 v151, v39, v47, s[40:41]
	v_cndmask_b32_e64 v152, v40, v48, s[40:41]
	v_cndmask_b32_e64 v153, v41, v49, s[40:41]
	v_cndmask_b32_e64 v154, v38, v138, s[42:43]
	v_cndmask_b32_e64 v155, v39, v139, s[42:43]
	v_cndmask_b32_e64 v156, v40, v140, s[42:43]
	v_cndmask_b32_e64 v157, v41, v141, s[42:43]
	v_pk_fma_f32 v[122:123], v[38:39], v[118:119], v[102:103]
	v_pk_fma_f32 v[124:125], v[40:41], v[120:121], v[104:105]
	v_fmac_f32_dpp v122, v150, v126 row_ror:1 row_mask:0xf bank_mask:0xf
	v_fmac_f32_dpp v123, v151, v127 row_ror:1 row_mask:0xf bank_mask:0xf
	v_fmac_f32_dpp v124, v152, v128 row_ror:1 row_mask:0xf bank_mask:0xf
	v_fmac_f32_dpp v125, v153, v129 row_ror:1 row_mask:0xf bank_mask:0xf
	v_fmac_f32_dpp v122, v154, v110 row_ror:15 row_mask:0xf bank_mask:0xf
	v_fmac_f32_dpp v123, v155, v111 row_ror:15 row_mask:0xf bank_mask:0xf
	v_fmac_f32_dpp v124, v156, v112 row_ror:15 row_mask:0xf bank_mask:0xf
	v_fmac_f32_dpp v125, v157, v113 row_ror:15 row_mask:0xf bank_mask:0xf
	v_cndmask_b32_e64 v150, v34, v42, s[40:41]
	v_cndmask_b32_e64 v151, v35, v43, s[40:41]
	v_cndmask_b32_e64 v152, v36, v44, s[40:41]
	v_cndmask_b32_e64 v153, v37, v45, s[40:41]
	v_cndmask_b32_e64 v154, v34, v142, s[42:43]
	v_cndmask_b32_e64 v155, v35, v143, s[42:43]
	v_cndmask_b32_e64 v156, v36, v144, s[42:43]
	v_cndmask_b32_e64 v157, v37, v145, s[42:43]
	v_pk_fma_f32 v[158:159], v[34:35], v[114:115], v[98:99]
	v_pk_fma_f32 v[160:161], v[36:37], v[116:117], v[100:101]
	v_fmac_f32_dpp v158, v150, v146 row_ror:1 row_mask:0xf bank_mask:0xf
	v_fmac_f32_dpp v159, v151, v147 row_ror:1 row_mask:0xf bank_mask:0xf
	v_fmac_f32_dpp v160, v152, v148 row_ror:1 row_mask:0xf bank_mask:0xf
	v_fmac_f32_dpp v161, v153, v149 row_ror:1 row_mask:0xf bank_mask:0xf
	v_fmac_f32_dpp v158, v154, v106 row_ror:15 row_mask:0xf bank_mask:0xf
	v_fmac_f32_dpp v159, v155, v107 row_ror:15 row_mask:0xf bank_mask:0xf
	v_fmac_f32_dpp v160, v156, v108 row_ror:15 row_mask:0xf bank_mask:0xf
	v_fmac_f32_dpp v161, v157, v109 row_ror:15 row_mask:0xf bank_mask:0xf
	s_add_u32 s26, s22, 0x2c000
	s_addc_u32 s27, s23, 0
	s_waitcnt lgkmcnt(0)
	global_store_dwordx4 v234, v[236:239], s[26:27]
	s_cmp_eq_u32 s30, 1
	s_cbranch_scc1 .Lffn1c_5
	s_lshl_b32 s100, s30, 11
	s_add_i32 s100, s100, 0x1800
	v_add_u32_e32 v231, s100, v189
	ds_read_b128 v[138:141], v231 offset:0
	ds_read_b128 v[142:145], v231 offset:512
	s_branch .Lffn1c_6

.Lffn1c_6:
	v_exp_f32_e32 v172, v122
	v_exp_f32_e32 v173, v123
	v_exp_f32_e32 v174, v124
	v_exp_f32_e32 v175, v125
	v_pk_add_f32 v[172:173], v[172:173], v[232:233] op_sel_hi:[1,0]
	v_pk_add_f32 v[174:175], v[174:175], v[232:233] op_sel_hi:[1,0]
	v_rcp_f32_e32 v172, v172
	v_rcp_f32_e32 v173, v173
	v_rcp_f32_e32 v174, v174
	v_rcp_f32_e32 v175, v175
	v_pk_mul_f32 v[122:123], v[122:123], v[158:159]
	v_pk_mul_f32 v[124:125], v[124:125], v[160:161]
	v_pk_mul_f32 v[172:173], v[172:173], v[122:123]
	v_pk_mul_f32 v[174:175], v[174:175], v[124:125]
	v_cvt_pk_bf16_f32 v228, v172, v173
	v_cvt_pk_bf16_f32 v229, v174, v175
	ds_bpermute_b32 v236, v235, v246
	ds_bpermute_b32 v237, v235, v247
	ds_bpermute_b32 v238, v235, v228
	ds_bpermute_b32 v239, v235, v229
	s_waitcnt lgkmcnt(0)
	v_cndmask_b32_e64 v150, v94, v130, s[40:41]
	v_cndmask_b32_e64 v151, v95, v131, s[40:41]
	v_cndmask_b32_e64 v152, v96, v132, s[40:41]
	v_cndmask_b32_e64 v153, v97, v133, s[40:41]
	v_cndmask_b32_e64 v154, v94, v86, s[42:43]
	v_cndmask_b32_e64 v155, v95, v87, s[42:43]
	v_cndmask_b32_e64 v156, v96, v88, s[42:43]
	v_cndmask_b32_e64 v157, v97, v89, s[42:43]
	v_pk_fma_f32 v[122:123], v[94:95], v[198:199], v[220:221]
	v_pk_fma_f32 v[124:125], v[96:97], v[200:201], v[222:223]
	v_fmac_f32_dpp v122, v150, v190 row_ror:1 row_mask:0xf bank_mask:0xf
	v_fmac_f32_dpp v123, v151, v191 row_ror:1 row_mask:0xf bank_mask:0xf
	v_fmac_f32_dpp v124, v152, v192 row_ror:1 row_mask:0xf bank_mask:0xf
	v_fmac_f32_dpp v125, v153, v193 row_ror:1 row_mask:0xf bank_mask:0xf
	v_fmac_f32_dpp v122, v154, v212 row_ror:15 row_mask:0xf bank_mask:0xf
	v_fmac_f32_dpp v123, v155, v213 row_ror:15 row_mask:0xf bank_mask:0xf
	v_fmac_f32_dpp v124, v156, v214 row_ror:15 row_mask:0xf bank_mask:0xf
	v_fmac_f32_dpp v125, v157, v215 row_ror:15 row_mask:0xf bank_mask:0xf
	v_cndmask_b32_e64 v150, v90, v134, s[40:41]
	v_cndmask_b32_e64 v151, v91, v135, s[40:41]
	v_cndmask_b32_e64 v152, v92, v136, s[40:41]
	v_cndmask_b32_e64 v153, v93, v137, s[40:41]
	v_cndmask_b32_e64 v154, v90, v82, s[42:43]
	v_cndmask_b32_e64 v155, v91, v83, s[42:43]
	v_cndmask_b32_e64 v156, v92, v84, s[42:43]
	v_cndmask_b32_e64 v157, v93, v85, s[42:43]
	v_pk_fma_f32 v[158:159], v[90:91], v[208:209], v[224:225]
	v_pk_fma_f32 v[160:161], v[92:93], v[210:211], v[226:227]
	v_fmac_f32_dpp v158, v150, v194 row_ror:1 row_mask:0xf bank_mask:0xf
	v_fmac_f32_dpp v159, v151, v195 row_ror:1 row_mask:0xf bank_mask:0xf
	v_fmac_f32_dpp v160, v152, v196 row_ror:1 row_mask:0xf bank_mask:0xf
	v_fmac_f32_dpp v161, v153, v197 row_ror:1 row_mask:0xf bank_mask:0xf
	v_fmac_f32_dpp v158, v154, v216 row_ror:15 row_mask:0xf bank_mask:0xf
	v_fmac_f32_dpp v159, v155, v217 row_ror:15 row_mask:0xf bank_mask:0xf
	v_fmac_f32_dpp v160, v156, v218 row_ror:15 row_mask:0xf bank_mask:0xf
	v_fmac_f32_dpp v161, v157, v219 row_ror:15 row_mask:0xf bank_mask:0xf
	s_add_u32 s26, s22, 0x42000
	s_addc_u32 s27, s23, 0
	s_waitcnt lgkmcnt(0)
	global_store_dwordx4 v234, v[236:239], s[26:27]
	s_lshl_b32 s100, s30, 11
	s_add_i32 s100, s100, 0xc00
	v_add_u32_e32 v231, s100, v189
	ds_read_b128 v[130:133], v231 offset:16
	ds_read_b128 v[134:137], v231 offset:528
	v_exp_f32_e32 v172, v122
	v_exp_f32_e32 v173, v123
	v_exp_f32_e32 v174, v124
	v_exp_f32_e32 v175, v125
	v_pk_add_f32 v[172:173], v[172:173], v[232:233] op_sel_hi:[1,0]
	v_pk_add_f32 v[174:175], v[174:175], v[232:233] op_sel_hi:[1,0]
	v_rcp_f32_e32 v172, v172
	v_rcp_f32_e32 v173, v173
	v_rcp_f32_e32 v174, v174
	v_rcp_f32_e32 v175, v175
	v_pk_mul_f32 v[122:123], v[122:123], v[158:159]
	v_pk_mul_f32 v[124:125], v[124:125], v[160:161]
	v_pk_mul_f32 v[172:173], v[172:173], v[122:123]
	v_pk_mul_f32 v[174:175], v[174:175], v[124:125]
	v_cvt_pk_bf16_f32 v240, v172, v173
	v_cvt_pk_bf16_f32 v241, v174, v175
	v_cndmask_b32_e64 v150, v86, v94, s[40:41]
	v_cndmask_b32_e64 v151, v87, v95, s[40:41]
	v_cndmask_b32_e64 v152, v88, v96, s[40:41]
	v_cndmask_b32_e64 v153, v89, v97, s[40:41]
	v_cndmask_b32_e64 v154, v86, v78, s[42:43]
	v_cndmask_b32_e64 v155, v87, v79, s[42:43]
	v_cndmask_b32_e64 v156, v88, v80, s[42:43]
	v_cndmask_b32_e64 v157, v89, v81, s[42:43]
	v_pk_fma_f32 v[122:123], v[86:87], v[198:199], v[220:221]
	v_pk_fma_f32 v[124:125], v[88:89], v[200:201], v[222:223]
	v_fmac_f32_dpp v122, v150, v190 row_ror:1 row_mask:0xf bank_mask:0xf
	v_fmac_f32_dpp v123, v151, v191 row_ror:1 row_mask:0xf bank_mask:0xf
	v_fmac_f32_dpp v124, v152, v192 row_ror:1 row_mask:0xf bank_mask:0xf
	v_fmac_f32_dpp v125, v153, v193 row_ror:1 row_mask:0xf bank_mask:0xf
	v_fmac_f32_dpp v122, v154, v212 row_ror:15 row_mask:0xf bank_mask:0xf
	v_fmac_f32_dpp v123, v155, v213 row_ror:15 row_mask:0xf bank_mask:0xf
	v_fmac_f32_dpp v124, v156, v214 row_ror:15 row_mask:0xf bank_mask:0xf
	v_fmac_f32_dpp v125, v157, v215 row_ror:15 row_mask:0xf bank_mask:0xf
	v_cndmask_b32_e64 v150, v82, v90, s[40:41]
	v_cndmask_b32_e64 v151, v83, v91, s[40:41]
	v_cndmask_b32_e64 v152, v84, v92, s[40:41]
	v_cndmask_b32_e64 v153, v85, v93, s[40:41]
	v_cndmask_b32_e64 v154, v82, v74, s[42:43]
	v_cndmask_b32_e64 v155, v83, v75, s[42:43]
	v_cndmask_b32_e64 v156, v84, v76, s[42:43]
	v_cndmask_b32_e64 v157, v85, v77, s[42:43]
	v_pk_fma_f32 v[158:159], v[82:83], v[208:209], v[224:225]
	v_pk_fma_f32 v[160:161], v[84:85], v[210:211], v[226:227]
	v_fmac_f32_dpp v158, v150, v194 row_ror:1 row_mask:0xf bank_mask:0xf
	v_fmac_f32_dpp v159, v151, v195 row_ror:1 row_mask:0xf bank_mask:0xf
	v_fmac_f32_dpp v160, v152, v196 row_ror:1 row_mask:0xf bank_mask:0xf
	v_fmac_f32_dpp v161, v153, v197 row_ror:1 row_mask:0xf bank_mask:0xf
	v_fmac_f32_dpp v158, v154, v216 row_ror:15 row_mask:0xf bank_mask:0xf
	v_fmac_f32_dpp v159, v155, v217 row_ror:15 row_mask:0xf bank_mask:0xf
	v_fmac_f32_dpp v160, v156, v218 row_ror:15 row_mask:0xf bank_mask:0xf
	v_fmac_f32_dpp v161, v157, v219 row_ror:15 row_mask:0xf bank_mask:0xf
	v_exp_f32_e32 v172, v122
	v_exp_f32_e32 v173, v123
	v_exp_f32_e32 v174, v124
	v_exp_f32_e32 v175, v125
	v_pk_add_f32 v[172:173], v[172:173], v[232:233] op_sel_hi:[1,0]
	v_pk_add_f32 v[174:175], v[174:175], v[232:233] op_sel_hi:[1,0]
	v_rcp_f32_e32 v172, v172
	v_rcp_f32_e32 v173, v173
	v_rcp_f32_e32 v174, v174
	v_rcp_f32_e32 v175, v175
	v_pk_mul_f32 v[122:123], v[122:123], v[158:159]
	v_pk_mul_f32 v[124:125], v[124:125], v[160:161]
	v_pk_mul_f32 v[172:173], v[172:173], v[122:123]
	v_pk_mul_f32 v[174:175], v[174:175], v[124:125]
	v_cvt_pk_bf16_f32 v242, v172, v173
	v_cvt_pk_bf16_f32 v243, v174, v175
	v_cndmask_b32_e64 v150, v78, v86, s[40:41]
	v_cndmask_b32_e64 v151, v79, v87, s[40:41]
	v_cndmask_b32_e64 v152, v80, v88, s[40:41]
	v_cndmask_b32_e64 v153, v81, v89, s[40:41]
	v_cndmask_b32_e64 v154, v78, v70, s[42:43]
	v_cndmask_b32_e64 v155, v79, v71, s[42:43]
	v_cndmask_b32_e64 v156, v80, v72, s[42:43]
	v_cndmask_b32_e64 v157, v81, v73, s[42:43]
	v_pk_fma_f32 v[122:123], v[78:79], v[198:199], v[220:221]
	v_pk_fma_f32 v[124:125], v[80:81], v[200:201], v[222:223]
	v_fmac_f32_dpp v122, v150, v190 row_ror:1 row_mask:0xf bank_mask:0xf
	v_fmac_f32_dpp v123, v151, v191 row_ror:1 row_mask:0xf bank_mask:0xf
	v_fmac_f32_dpp v124, v152, v192 row_ror:1 row_mask:0xf bank_mask:0xf
	v_fmac_f32_dpp v125, v153, v193 row_ror:1 row_mask:0xf bank_mask:0xf
	v_fmac_f32_dpp v122, v154, v212 row_ror:15 row_mask:0xf bank_mask:0xf
	v_fmac_f32_dpp v123, v155, v213 row_ror:15 row_mask:0xf bank_mask:0xf
	v_fmac_f32_dpp v124, v156, v214 row_ror:15 row_mask:0xf bank_mask:0xf
	v_fmac_f32_dpp v125, v157, v215 row_ror:15 row_mask:0xf bank_mask:0xf
	v_cndmask_b32_e64 v150, v74, v82, s[40:41]
	v_cndmask_b32_e64 v151, v75, v83, s[40:41]
	v_cndmask_b32_e64 v152, v76, v84, s[40:41]
	v_cndmask_b32_e64 v153, v77, v85, s[40:41]
	v_cndmask_b32_e64 v154, v74, v66, s[42:43]
	v_cndmask_b32_e64 v155, v75, v67, s[42:43]
	v_cndmask_b32_e64 v156, v76, v68, s[42:43]
	v_cndmask_b32_e64 v157, v77, v69, s[42:43]
	v_pk_fma_f32 v[158:159], v[74:75], v[208:209], v[224:225]
	v_pk_fma_f32 v[160:161], v[76:77], v[210:211], v[226:227]
	v_fmac_f32_dpp v158, v150, v194 row_ror:1 row_mask:0xf bank_mask:0xf
	v_fmac_f32_dpp v159, v151, v195 row_ror:1 row_mask:0xf bank_mask:0xf
	v_fmac_f32_dpp v160, v152, v196 row_ror:1 row_mask:0xf bank_mask:0xf
	v_fmac_f32_dpp v161, v153, v197 row_ror:1 row_mask:0xf bank_mask:0xf
	v_fmac_f32_dpp v158, v154, v216 row_ror:15 row_mask:0xf bank_mask:0xf
	v_fmac_f32_dpp v159, v155, v217 row_ror:15 row_mask:0xf bank_mask:0xf
	v_fmac_f32_dpp v160, v156, v218 row_ror:15 row_mask:0xf bank_mask:0xf
	v_fmac_f32_dpp v161, v157, v219 row_ror:15 row_mask:0xf bank_mask:0xf
	v_exp_f32_e32 v172, v122
	v_exp_f32_e32 v173, v123
	v_exp_f32_e32 v174, v124
	v_exp_f32_e32 v175, v125
	v_pk_add_f32 v[172:173], v[172:173], v[232:233] op_sel_hi:[1,0]
	v_pk_add_f32 v[174:175], v[174:175], v[232:233] op_sel_hi:[1,0]
	v_rcp_f32_e32 v172, v172
	v_rcp_f32_e32 v173, v173
	v_rcp_f32_e32 v174, v174
	v_rcp_f32_e32 v175, v175
	v_pk_mul_f32 v[122:123], v[122:123], v[158:159]
	v_pk_mul_f32 v[124:125], v[124:125], v[160:161]
	v_pk_mul_f32 v[172:173], v[172:173], v[122:123]
	v_pk_mul_f32 v[174:175], v[174:175], v[124:125]
	v_cvt_pk_bf16_f32 v244, v172, v173
	v_cvt_pk_bf16_f32 v245, v174, v175
	s_waitcnt lgkmcnt(0)
	v_cndmask_b32_e64 v150, v70, v78, s[40:41]
	v_cndmask_b32_e64 v151, v71, v79, s[40:41]
	v_cndmask_b32_e64 v152, v72, v80, s[40:41]
	v_cndmask_b32_e64 v153, v73, v81, s[40:41]
	v_cndmask_b32_e64 v154, v70, v138, s[42:43]
	v_cndmask_b32_e64 v155, v71, v139, s[42:43]
	v_cndmask_b32_e64 v156, v72, v140, s[42:43]
	v_cndmask_b32_e64 v157, v73, v141, s[42:43]
	v_pk_fma_f32 v[122:123], v[70:71], v[198:199], v[220:221]
	v_pk_fma_f32 v[124:125], v[72:73], v[200:201], v[222:223]
	v_fmac_f32_dpp v122, v150, v190 row_ror:1 row_mask:0xf bank_mask:0xf
	v_fmac_f32_dpp v123, v151, v191 row_ror:1 row_mask:0xf bank_mask:0xf
	v_fmac_f32_dpp v124, v152, v192 row_ror:1 row_mask:0xf bank_mask:0xf
	v_fmac_f32_dpp v125, v153, v193 row_ror:1 row_mask:0xf bank_mask:0xf
	v_fmac_f32_dpp v122, v154, v212 row_ror:15 row_mask:0xf bank_mask:0xf
	v_fmac_f32_dpp v123, v155, v213 row_ror:15 row_mask:0xf bank_mask:0xf
	v_fmac_f32_dpp v124, v156, v214 row_ror:15 row_mask:0xf bank_mask:0xf
	v_fmac_f32_dpp v125, v157, v215 row_ror:15 row_mask:0xf bank_mask:0xf
	v_cndmask_b32_e64 v150, v66, v74, s[40:41]
	v_cndmask_b32_e64 v151, v67, v75, s[40:41]
	v_cndmask_b32_e64 v152, v68, v76, s[40:41]
	v_cndmask_b32_e64 v153, v69, v77, s[40:41]
	v_cndmask_b32_e64 v154, v66, v142, s[42:43]
	v_cndmask_b32_e64 v155, v67, v143, s[42:43]
	v_cndmask_b32_e64 v156, v68, v144, s[42:43]
	v_cndmask_b32_e64 v157, v69, v145, s[42:43]
	v_pk_fma_f32 v[158:159], v[66:67], v[208:209], v[224:225]
	v_pk_fma_f32 v[160:161], v[68:69], v[210:211], v[226:227]
	v_fmac_f32_dpp v158, v150, v194 row_ror:1 row_mask:0xf bank_mask:0xf
	v_fmac_f32_dpp v159, v151, v195 row_ror:1 row_mask:0xf bank_mask:0xf
	v_fmac_f32_dpp v160, v152, v196 row_ror:1 row_mask:0xf bank_mask:0xf
	v_fmac_f32_dpp v161, v153, v197 row_ror:1 row_mask:0xf bank_mask:0xf
	v_fmac_f32_dpp v158, v154, v216 row_ror:15 row_mask:0xf bank_mask:0xf
	v_fmac_f32_dpp v159, v155, v217 row_ror:15 row_mask:0xf bank_mask:0xf
	v_fmac_f32_dpp v160, v156, v218 row_ror:15 row_mask:0xf bank_mask:0xf
	v_fmac_f32_dpp v161, v157, v219 row_ror:15 row_mask:0xf bank_mask:0xf
	s_cmp_eq_u32 s30, 1
	s_cbranch_scc1 .Lffn1c_7
	s_lshl_b32 s100, s30, 11
	s_add_i32 s100, s100, 0x1800
	v_add_u32_e32 v231, s100, v189
	ds_read_b128 v[138:141], v231 offset:16
	ds_read_b128 v[142:145], v231 offset:528
	s_branch .Lffn1c_8

.Lffn1c_8:
	v_exp_f32_e32 v172, v122
	v_exp_f32_e32 v173, v123
	v_exp_f32_e32 v174, v124
	v_exp_f32_e32 v175, v125
	v_pk_add_f32 v[172:173], v[172:173], v[232:233] op_sel_hi:[1,0]
	v_pk_add_f32 v[174:175], v[174:175], v[232:233] op_sel_hi:[1,0]
	v_rcp_f32_e32 v172, v172
	v_rcp_f32_e32 v173, v173
	v_rcp_f32_e32 v174, v174
	v_rcp_f32_e32 v175, v175
	v_pk_mul_f32 v[122:123], v[122:123], v[158:159]
	v_pk_mul_f32 v[124:125], v[124:125], v[160:161]
	v_pk_mul_f32 v[172:173], v[172:173], v[122:123]
	v_pk_mul_f32 v[174:175], v[174:175], v[124:125]
	v_cvt_pk_bf16_f32 v246, v172, v173
	v_cvt_pk_bf16_f32 v247, v174, v175
	s_waitcnt lgkmcnt(0)
	v_cndmask_b32_e64 v150, v30, v130, s[40:41]
	v_cndmask_b32_e64 v151, v31, v131, s[40:41]
	v_cndmask_b32_e64 v152, v32, v132, s[40:41]
	v_cndmask_b32_e64 v153, v33, v133, s[40:41]
	v_cndmask_b32_e64 v154, v30, v22, s[42:43]
	v_cndmask_b32_e64 v155, v31, v23, s[42:43]
	v_cndmask_b32_e64 v156, v32, v24, s[42:43]
	v_cndmask_b32_e64 v157, v33, v25, s[42:43]
	v_pk_fma_f32 v[122:123], v[30:31], v[118:119], v[102:103]
	v_pk_fma_f32 v[124:125], v[32:33], v[120:121], v[104:105]
	v_fmac_f32_dpp v122, v150, v126 row_ror:1 row_mask:0xf bank_mask:0xf
	v_fmac_f32_dpp v123, v151, v127 row_ror:1 row_mask:0xf bank_mask:0xf
	v_fmac_f32_dpp v124, v152, v128 row_ror:1 row_mask:0xf bank_mask:0xf
	v_fmac_f32_dpp v125, v153, v129 row_ror:1 row_mask:0xf bank_mask:0xf
	v_fmac_f32_dpp v122, v154, v110 row_ror:15 row_mask:0xf bank_mask:0xf
	v_fmac_f32_dpp v123, v155, v111 row_ror:15 row_mask:0xf bank_mask:0xf
	v_fmac_f32_dpp v124, v156, v112 row_ror:15 row_mask:0xf bank_mask:0xf
	v_fmac_f32_dpp v125, v157, v113 row_ror:15 row_mask:0xf bank_mask:0xf
	v_cndmask_b32_e64 v150, v26, v134, s[40:41]
	v_cndmask_b32_e64 v151, v27, v135, s[40:41]
	v_cndmask_b32_e64 v152, v28, v136, s[40:41]
	v_cndmask_b32_e64 v153, v29, v137, s[40:41]
	v_cndmask_b32_e64 v154, v26, v18, s[42:43]
	v_cndmask_b32_e64 v155, v27, v19, s[42:43]
	v_cndmask_b32_e64 v156, v28, v20, s[42:43]
	v_cndmask_b32_e64 v157, v29, v21, s[42:43]
	v_pk_fma_f32 v[158:159], v[26:27], v[114:115], v[98:99]
	v_pk_fma_f32 v[160:161], v[28:29], v[116:117], v[100:101]
	v_fmac_f32_dpp v158, v150, v146 row_ror:1 row_mask:0xf bank_mask:0xf
	v_fmac_f32_dpp v159, v151, v147 row_ror:1 row_mask:0xf bank_mask:0xf
	v_fmac_f32_dpp v160, v152, v148 row_ror:1 row_mask:0xf bank_mask:0xf
	v_fmac_f32_dpp v161, v153, v149 row_ror:1 row_mask:0xf bank_mask:0xf
	v_fmac_f32_dpp v158, v154, v106 row_ror:15 row_mask:0xf bank_mask:0xf
	v_fmac_f32_dpp v159, v155, v107 row_ror:15 row_mask:0xf bank_mask:0xf
	v_fmac_f32_dpp v160, v156, v108 row_ror:15 row_mask:0xf bank_mask:0xf
	v_fmac_f32_dpp v161, v157, v109 row_ror:15 row_mask:0xf bank_mask:0xf
	v_exp_f32_e32 v172, v122
	v_exp_f32_e32 v173, v123
	v_exp_f32_e32 v174, v124
	v_exp_f32_e32 v175, v125
	v_pk_add_f32 v[172:173], v[172:173], v[232:233] op_sel_hi:[1,0]
	v_pk_add_f32 v[174:175], v[174:175], v[232:233] op_sel_hi:[1,0]
	v_rcp_f32_e32 v172, v172
	v_rcp_f32_e32 v173, v173
	v_rcp_f32_e32 v174, v174
	v_rcp_f32_e32 v175, v175
	v_pk_mul_f32 v[122:123], v[122:123], v[158:159]
	v_pk_mul_f32 v[124:125], v[124:125], v[160:161]
	v_pk_mul_f32 v[172:173], v[172:173], v[122:123]
	v_pk_mul_f32 v[174:175], v[174:175], v[124:125]
	v_cvt_pk_bf16_f32 v228, v172, v173
	v_cvt_pk_bf16_f32 v229, v174, v175
	ds_bpermute_b32 v236, v235, v240
	ds_bpermute_b32 v237, v235, v241
	ds_bpermute_b32 v238, v235, v228
	ds_bpermute_b32 v239, v235, v229
	v_cndmask_b32_e64 v150, v22, v30, s[40:41]
	v_cndmask_b32_e64 v151, v23, v31, s[40:41]
	v_cndmask_b32_e64 v152, v24, v32, s[40:41]
	v_cndmask_b32_e64 v153, v25, v33, s[40:41]
	v_cndmask_b32_e64 v154, v22, v14, s[42:43]
	v_cndmask_b32_e64 v155, v23, v15, s[42:43]
	v_cndmask_b32_e64 v156, v24, v16, s[42:43]
	v_cndmask_b32_e64 v157, v25, v17, s[42:43]
	v_pk_fma_f32 v[122:123], v[22:23], v[118:119], v[102:103]
	v_pk_fma_f32 v[124:125], v[24:25], v[120:121], v[104:105]
	v_fmac_f32_dpp v122, v150, v126 row_ror:1 row_mask:0xf bank_mask:0xf
	v_fmac_f32_dpp v123, v151, v127 row_ror:1 row_mask:0xf bank_mask:0xf
	v_fmac_f32_dpp v124, v152, v128 row_ror:1 row_mask:0xf bank_mask:0xf
	v_fmac_f32_dpp v125, v153, v129 row_ror:1 row_mask:0xf bank_mask:0xf
	v_fmac_f32_dpp v122, v154, v110 row_ror:15 row_mask:0xf bank_mask:0xf
	v_fmac_f32_dpp v123, v155, v111 row_ror:15 row_mask:0xf bank_mask:0xf
	v_fmac_f32_dpp v124, v156, v112 row_ror:15 row_mask:0xf bank_mask:0xf
	v_fmac_f32_dpp v125, v157, v113 row_ror:15 row_mask:0xf bank_mask:0xf
	v_cndmask_b32_e64 v150, v18, v26, s[40:41]
	v_cndmask_b32_e64 v151, v19, v27, s[40:41]
	v_cndmask_b32_e64 v152, v20, v28, s[40:41]
	v_cndmask_b32_e64 v153, v21, v29, s[40:41]
	v_cndmask_b32_e64 v154, v18, v10, s[42:43]
	v_cndmask_b32_e64 v155, v19, v11, s[42:43]
	v_cndmask_b32_e64 v156, v20, v12, s[42:43]
	v_cndmask_b32_e64 v157, v21, v13, s[42:43]
	v_pk_fma_f32 v[158:159], v[18:19], v[114:115], v[98:99]
	v_pk_fma_f32 v[160:161], v[20:21], v[116:117], v[100:101]
	v_fmac_f32_dpp v158, v150, v146 row_ror:1 row_mask:0xf bank_mask:0xf
	v_fmac_f32_dpp v159, v151, v147 row_ror:1 row_mask:0xf bank_mask:0xf
	v_fmac_f32_dpp v160, v152, v148 row_ror:1 row_mask:0xf bank_mask:0xf
	v_fmac_f32_dpp v161, v153, v149 row_ror:1 row_mask:0xf bank_mask:0xf
	v_fmac_f32_dpp v158, v154, v106 row_ror:15 row_mask:0xf bank_mask:0xf
	v_fmac_f32_dpp v159, v155, v107 row_ror:15 row_mask:0xf bank_mask:0xf
	v_fmac_f32_dpp v160, v156, v108 row_ror:15 row_mask:0xf bank_mask:0xf
	v_fmac_f32_dpp v161, v157, v109 row_ror:15 row_mask:0xf bank_mask:0xf
	s_add_u32 s26, s22, 0xb0000
	s_addc_u32 s27, s23, 0
	s_waitcnt lgkmcnt(0)
	global_store_dwordx4 v234, v[236:239], s[26:27]
	v_exp_f32_e32 v172, v122
	v_exp_f32_e32 v173, v123
	v_exp_f32_e32 v174, v124
	v_exp_f32_e32 v175, v125
	v_pk_add_f32 v[172:173], v[172:173], v[232:233] op_sel_hi:[1,0]
	v_pk_add_f32 v[174:175], v[174:175], v[232:233] op_sel_hi:[1,0]
	v_rcp_f32_e32 v172, v172
	v_rcp_f32_e32 v173, v173
	v_rcp_f32_e32 v174, v174
	v_rcp_f32_e32 v175, v175
	v_pk_mul_f32 v[122:123], v[122:123], v[158:159]
	v_pk_mul_f32 v[124:125], v[124:125], v[160:161]
	v_pk_mul_f32 v[172:173], v[172:173], v[122:123]
	v_pk_mul_f32 v[174:175], v[174:175], v[124:125]
	v_cvt_pk_bf16_f32 v228, v172, v173
	v_cvt_pk_bf16_f32 v229, v174, v175
	ds_bpermute_b32 v236, v235, v242
	ds_bpermute_b32 v237, v235, v243
	ds_bpermute_b32 v238, v235, v228
	ds_bpermute_b32 v239, v235, v229
	v_cndmask_b32_e64 v150, v14, v22, s[40:41]
	v_cndmask_b32_e64 v151, v15, v23, s[40:41]
	v_cndmask_b32_e64 v152, v16, v24, s[40:41]
	v_cndmask_b32_e64 v153, v17, v25, s[40:41]
	v_cndmask_b32_e64 v154, v14, v6, s[42:43]
	v_cndmask_b32_e64 v155, v15, v7, s[42:43]
	v_cndmask_b32_e64 v156, v16, v8, s[42:43]
	v_cndmask_b32_e64 v157, v17, v9, s[42:43]
	v_pk_fma_f32 v[122:123], v[14:15], v[118:119], v[102:103]
	v_pk_fma_f32 v[124:125], v[16:17], v[120:121], v[104:105]
	v_fmac_f32_dpp v122, v150, v126 row_ror:1 row_mask:0xf bank_mask:0xf
	v_fmac_f32_dpp v123, v151, v127 row_ror:1 row_mask:0xf bank_mask:0xf
	v_fmac_f32_dpp v124, v152, v128 row_ror:1 row_mask:0xf bank_mask:0xf
	v_fmac_f32_dpp v125, v153, v129 row_ror:1 row_mask:0xf bank_mask:0xf
	v_fmac_f32_dpp v122, v154, v110 row_ror:15 row_mask:0xf bank_mask:0xf
	v_fmac_f32_dpp v123, v155, v111 row_ror:15 row_mask:0xf bank_mask:0xf
	v_fmac_f32_dpp v124, v156, v112 row_ror:15 row_mask:0xf bank_mask:0xf
	v_fmac_f32_dpp v125, v157, v113 row_ror:15 row_mask:0xf bank_mask:0xf
	v_cndmask_b32_e64 v150, v10, v18, s[40:41]
	v_cndmask_b32_e64 v151, v11, v19, s[40:41]
	v_cndmask_b32_e64 v152, v12, v20, s[40:41]
	v_cndmask_b32_e64 v153, v13, v21, s[40:41]
	v_cndmask_b32_e64 v154, v10, v2, s[42:43]
	v_cndmask_b32_e64 v155, v11, v3, s[42:43]
	v_cndmask_b32_e64 v156, v12, v4, s[42:43]
	v_cndmask_b32_e64 v157, v13, v5, s[42:43]
	v_pk_fma_f32 v[158:159], v[10:11], v[114:115], v[98:99]
	v_pk_fma_f32 v[160:161], v[12:13], v[116:117], v[100:101]
	v_fmac_f32_dpp v158, v150, v146 row_ror:1 row_mask:0xf bank_mask:0xf
	v_fmac_f32_dpp v159, v151, v147 row_ror:1 row_mask:0xf bank_mask:0xf
	v_fmac_f32_dpp v160, v152, v148 row_ror:1 row_mask:0xf bank_mask:0xf
	v_fmac_f32_dpp v161, v153, v149 row_ror:1 row_mask:0xf bank_mask:0xf
	v_fmac_f32_dpp v158, v154, v106 row_ror:15 row_mask:0xf bank_mask:0xf
	v_fmac_f32_dpp v159, v155, v107 row_ror:15 row_mask:0xf bank_mask:0xf
	v_fmac_f32_dpp v160, v156, v108 row_ror:15 row_mask:0xf bank_mask:0xf
	v_fmac_f32_dpp v161, v157, v109 row_ror:15 row_mask:0xf bank_mask:0xf
	s_add_u32 s26, s22, 0xc6000
	s_addc_u32 s27, s23, 0
	s_waitcnt lgkmcnt(0)
	global_store_dwordx4 v234, v[236:239], s[26:27]
	v_exp_f32_e32 v172, v122
	v_exp_f32_e32 v173, v123
	v_exp_f32_e32 v174, v124
	v_exp_f32_e32 v175, v125
	v_pk_add_f32 v[172:173], v[172:173], v[232:233] op_sel_hi:[1,0]
	v_pk_add_f32 v[174:175], v[174:175], v[232:233] op_sel_hi:[1,0]
	v_rcp_f32_e32 v172, v172
	v_rcp_f32_e32 v173, v173
	v_rcp_f32_e32 v174, v174
	v_rcp_f32_e32 v175, v175
	v_pk_mul_f32 v[122:123], v[122:123], v[158:159]
	v_pk_mul_f32 v[124:125], v[124:125], v[160:161]
	v_pk_mul_f32 v[172:173], v[172:173], v[122:123]
	v_pk_mul_f32 v[174:175], v[174:175], v[124:125]
	v_cvt_pk_bf16_f32 v228, v172, v173
	v_cvt_pk_bf16_f32 v229, v174, v175
	ds_bpermute_b32 v236, v235, v244
	ds_bpermute_b32 v237, v235, v245
	ds_bpermute_b32 v238, v235, v228
	ds_bpermute_b32 v239, v235, v229
	s_waitcnt lgkmcnt(0)
	v_cndmask_b32_e64 v150, v6, v14, s[40:41]
	v_cndmask_b32_e64 v151, v7, v15, s[40:41]
	v_cndmask_b32_e64 v152, v8, v16, s[40:41]
	v_cndmask_b32_e64 v153, v9, v17, s[40:41]
	v_cndmask_b32_e64 v154, v6, v138, s[42:43]
	v_cndmask_b32_e64 v155, v7, v139, s[42:43]
	v_cndmask_b32_e64 v156, v8, v140, s[42:43]
	v_cndmask_b32_e64 v157, v9, v141, s[42:43]
	v_pk_fma_f32 v[122:123], v[6:7], v[118:119], v[102:103]
	v_pk_fma_f32 v[124:125], v[8:9], v[120:121], v[104:105]
	v_fmac_f32_dpp v122, v150, v126 row_ror:1 row_mask:0xf bank_mask:0xf
	v_fmac_f32_dpp v123, v151, v127 row_ror:1 row_mask:0xf bank_mask:0xf
	v_fmac_f32_dpp v124, v152, v128 row_ror:1 row_mask:0xf bank_mask:0xf
	v_fmac_f32_dpp v125, v153, v129 row_ror:1 row_mask:0xf bank_mask:0xf
	v_fmac_f32_dpp v122, v154, v110 row_ror:15 row_mask:0xf bank_mask:0xf
	v_fmac_f32_dpp v123, v155, v111 row_ror:15 row_mask:0xf bank_mask:0xf
	v_fmac_f32_dpp v124, v156, v112 row_ror:15 row_mask:0xf bank_mask:0xf
	v_fmac_f32_dpp v125, v157, v113 row_ror:15 row_mask:0xf bank_mask:0xf
	v_cndmask_b32_e64 v150, v2, v10, s[40:41]
	v_cndmask_b32_e64 v151, v3, v11, s[40:41]
	v_cndmask_b32_e64 v152, v4, v12, s[40:41]
	v_cndmask_b32_e64 v153, v5, v13, s[40:41]
	v_cndmask_b32_e64 v154, v2, v142, s[42:43]
	v_cndmask_b32_e64 v155, v3, v143, s[42:43]
	v_cndmask_b32_e64 v156, v4, v144, s[42:43]
	v_cndmask_b32_e64 v157, v5, v145, s[42:43]
	v_pk_fma_f32 v[158:159], v[2:3], v[114:115], v[98:99]
	v_pk_fma_f32 v[160:161], v[4:5], v[116:117], v[100:101]
	v_fmac_f32_dpp v158, v150, v146 row_ror:1 row_mask:0xf bank_mask:0xf
	v_fmac_f32_dpp v159, v151, v147 row_ror:1 row_mask:0xf bank_mask:0xf
	v_fmac_f32_dpp v160, v152, v148 row_ror:1 row_mask:0xf bank_mask:0xf
	v_fmac_f32_dpp v161, v153, v149 row_ror:1 row_mask:0xf bank_mask:0xf
	v_fmac_f32_dpp v158, v154, v106 row_ror:15 row_mask:0xf bank_mask:0xf
	v_fmac_f32_dpp v159, v155, v107 row_ror:15 row_mask:0xf bank_mask:0xf
	v_fmac_f32_dpp v160, v156, v108 row_ror:15 row_mask:0xf bank_mask:0xf
	v_fmac_f32_dpp v161, v157, v109 row_ror:15 row_mask:0xf bank_mask:0xf
	s_add_u32 s26, s22, 0xdc000
	s_addc_u32 s27, s23, 0
	s_waitcnt lgkmcnt(0)
	global_store_dwordx4 v234, v[236:239], s[26:27]
	v_exp_f32_e32 v172, v122
	v_exp_f32_e32 v173, v123
	v_exp_f32_e32 v174, v124
	v_exp_f32_e32 v175, v125
	v_pk_add_f32 v[172:173], v[172:173], v[232:233] op_sel_hi:[1,0]
	v_pk_add_f32 v[174:175], v[174:175], v[232:233] op_sel_hi:[1,0]
	v_rcp_f32_e32 v172, v172
	v_rcp_f32_e32 v173, v173
	v_rcp_f32_e32 v174, v174
	v_rcp_f32_e32 v175, v175
	v_pk_mul_f32 v[122:123], v[122:123], v[158:159]
	v_pk_mul_f32 v[124:125], v[124:125], v[160:161]
	v_pk_mul_f32 v[172:173], v[172:173], v[122:123]
	v_pk_mul_f32 v[174:175], v[174:175], v[124:125]
	v_cvt_pk_bf16_f32 v228, v172, v173
	v_cvt_pk_bf16_f32 v229, v174, v175
	ds_bpermute_b32 v236, v235, v246
	ds_bpermute_b32 v237, v235, v247
	ds_bpermute_b32 v238, v235, v228
	ds_bpermute_b32 v239, v235, v229
	s_add_u32 s26, s22, 0xf2000
	s_addc_u32 s27, s23, 0
	s_waitcnt lgkmcnt(0)
	global_store_dwordx4 v234, v[236:239], s[26:27]
	s_and_b64 vcc, exec, s[38:39]
	s_mov_b64 s[0:1], -1
	s_cbranch_vccnz .LBB0_64
	s_andn2_b64 vcc, exec, s[6:7]
	s_cbranch_vccnz .LBB0_63
	s_barrier
	s_branch .LBB0_63
